# LN normalize: all 8 row mean/rstd pairs read from LDS in one batch (on peeled-loop version)
# baseline (speedup 1.0000x reference)
.LBB0_722:
	s_or_b64 exec, exec, s[50:51]
	v_lshlrev_b64 v[128:129], 2, v[186:187]
	s_waitcnt lgkmcnt(0)
	s_barrier
	v_lshl_add_u64 v[132:133], s[30:31], 0, v[128:129]
	v_lshl_add_u64 v[140:141], s[34:35], 0, v[128:129]
	s_waitcnt lgkmcnt(0)
	global_load_dwordx4 v[128:131], v[132:133], off offset:528
	global_load_dwordx4 v[136:139], v[132:133], off offset:512
	s_nop 0
	global_load_dwordx4 v[132:135], v[140:141], off offset:528
	s_nop 0
	global_load_dwordx4 v[140:143], v[140:141], off offset:512
	ds_read_b64 v[160:161], v209
	ds_read_b64 v[168:169], v211
	ds_read_b64 v[170:171], v213
	ds_read_b64 v[172:173], v215
	ds_read_b64 v[174:175], v217
	ds_read_b64 v[224:225], v219
	ds_read_b64 v[226:227], v221
	ds_read_b64 v[238:239], v223
	v_lshlrev_b64 v[162:163], 10, v[188:189]
	v_lshl_add_u64 v[162:163], v[162:163], 0, v[186:187]
	s_and_b64 vcc, exec, s[44:45]
	v_lshl_add_u64 v[164:165], v[162:163], 2, s[28:29]
	s_waitcnt lgkmcnt(0)
	v_pk_add_f32 v[74:75], v[74:75], v[160:161] op_sel_hi:[1,0] neg_lo:[0,1] neg_hi:[0,1]
	v_pk_add_f32 v[72:73], v[72:73], v[160:161] op_sel_hi:[1,0] neg_lo:[0,1] neg_hi:[0,1]
	v_pk_add_f32 v[70:71], v[70:71], v[160:161] op_sel_hi:[1,0] neg_lo:[0,1] neg_hi:[0,1]
	v_pk_add_f32 v[68:69], v[68:69], v[160:161] op_sel_hi:[1,0] neg_lo:[0,1] neg_hi:[0,1]
	v_pk_mul_f32 v[72:73], v[160:161], v[72:73] op_sel:[1,0]
	v_pk_mul_f32 v[74:75], v[160:161], v[74:75] op_sel:[1,0]
	v_pk_mul_f32 v[68:69], v[160:161], v[68:69] op_sel:[1,0]
	v_pk_mul_f32 v[70:71], v[160:161], v[70:71] op_sel:[1,0]
	s_waitcnt vmcnt(5)
	v_pk_fma_f32 v[68:69], v[144:145], v[68:69], v[148:149]
	s_waitcnt vmcnt(4)
	v_pk_fma_f32 v[74:75], v[154:155], v[74:75], v[158:159]
	v_pk_fma_f32 v[72:73], v[152:153], v[72:73], v[156:157]
	v_pk_fma_f32 v[70:71], v[146:147], v[70:71], v[150:151]
	s_cbranch_vccz .LBB0_724
	global_store_dwordx4 v[164:165], v[72:75], off
	global_store_dwordx4 v[164:165], v[68:71], off offset:16

.LBB0_726:
	s_nop 0
	v_cvt_pk_bf16_f32 v20, v20, v21
	v_cvt_pk_bf16_f32 v21, v22, v23
	v_cvt_pk_bf16_f32 v22, v16, v17
	v_mov_b64_e32 v[16:17], v[168:169]
	v_cvt_pk_bf16_f32 v23, v18, v19
	v_add_u32_e32 v18, s54, v210
	v_ashrrev_i32_e32 v19, 31, v18
	v_lshlrev_b64 v[18:19], 10, v[18:19]
	s_waitcnt lgkmcnt(0)
	v_pk_add_f32 v[14:15], v[14:15], v[16:17] op_sel_hi:[1,0] neg_lo:[0,1] neg_hi:[0,1]
	v_pk_add_f32 v[12:13], v[12:13], v[16:17] op_sel_hi:[1,0] neg_lo:[0,1] neg_hi:[0,1]
	v_pk_add_f32 v[10:11], v[10:11], v[16:17] op_sel_hi:[1,0] neg_lo:[0,1] neg_hi:[0,1]
	v_pk_add_f32 v[8:9], v[8:9], v[16:17] op_sel_hi:[1,0] neg_lo:[0,1] neg_hi:[0,1]
	global_store_dwordx4 v[68:69], v[20:23], off offset:256
	v_pk_mul_f32 v[12:13], v[16:17], v[12:13] op_sel:[1,0]
	v_pk_mul_f32 v[14:15], v[16:17], v[14:15] op_sel:[1,0]
	v_lshl_add_u64 v[20:21], v[18:19], 0, v[186:187]
	v_pk_mul_f32 v[8:9], v[16:17], v[8:9] op_sel:[1,0]
	v_pk_mul_f32 v[10:11], v[16:17], v[10:11] op_sel:[1,0]
	v_pk_fma_f32 v[14:15], v[154:155], v[14:15], v[158:159]
	v_pk_fma_f32 v[12:13], v[152:153], v[12:13], v[156:157]
	v_pk_fma_f32 v[10:11], v[146:147], v[10:11], v[150:151]
	v_pk_fma_f32 v[8:9], v[144:145], v[8:9], v[148:149]
	s_and_b64 vcc, exec, s[12:13]
	v_lshl_add_u64 v[18:19], v[20:21], 2, s[28:29]
	s_cbranch_vccnz .LBB0_728
	global_store_dwordx4 v[18:19], v[12:15], off
	global_store_dwordx4 v[18:19], v[8:11], off offset:16

.LBB0_730:
	s_nop 0
	v_cvt_pk_bf16_f32 v4, v4, v5
	v_cvt_pk_bf16_f32 v5, v6, v7
	v_cvt_pk_bf16_f32 v6, v0, v1
	v_cvt_pk_bf16_f32 v7, v2, v3
	global_store_dwordx4 v[8:9], v[4:7], off offset:256
	v_mov_b64_e32 v[8:9], v[170:171]
	v_add_u32_e32 v0, s54, v212
	v_ashrrev_i32_e32 v1, 31, v0
	v_lshlrev_b64 v[0:1], 10, v[0:1]
	v_lshl_add_u64 v[12:13], v[0:1], 0, v[186:187]
	s_waitcnt lgkmcnt(0)
	v_pk_add_f32 v[0:1], v[62:63], v[8:9] op_sel_hi:[1,0] neg_lo:[0,1] neg_hi:[0,1]
	v_pk_add_f32 v[2:3], v[60:61], v[8:9] op_sel_hi:[1,0] neg_lo:[0,1] neg_hi:[0,1]
	v_pk_mul_f32 v[4:5], v[8:9], v[2:3] op_sel:[1,0]
	v_pk_mul_f32 v[0:1], v[8:9], v[0:1] op_sel:[1,0]
	v_sub_f32_e32 v7, v57, v8
	v_pk_fma_f32 v[2:3], v[154:155], v[0:1], v[158:159]
	v_pk_fma_f32 v[0:1], v[152:153], v[4:5], v[156:157]
	v_pk_add_f32 v[4:5], v[58:59], v[8:9] op_sel_hi:[1,0] neg_lo:[0,1] neg_hi:[0,1]
	v_sub_f32_e32 v6, v56, v8
	v_pk_mul_f32 v[10:11], v[8:9], v[6:7] op_sel:[1,0]
	v_pk_mul_f32 v[4:5], v[8:9], v[4:5] op_sel:[1,0]
	s_and_b64 vcc, exec, s[12:13]
	v_pk_fma_f32 v[6:7], v[146:147], v[4:5], v[150:151]
	v_pk_fma_f32 v[4:5], v[144:145], v[10:11], v[148:149]
	v_lshl_add_u64 v[10:11], v[12:13], 2, s[28:29]
	s_cbranch_vccnz .LBB0_732
	global_store_dwordx4 v[10:11], v[0:3], off
	global_store_dwordx4 v[10:11], v[4:7], off offset:16

.LBB0_734:
	v_mov_b64_e32 v[8:9], v[172:173]
	v_cvt_pk_bf16_f32 v0, v0, v1
	v_cvt_pk_bf16_f32 v1, v2, v3
	v_cvt_pk_bf16_f32 v2, v4, v5
	v_cvt_pk_bf16_f32 v3, v6, v7
	global_store_dwordx4 v[12:13], v[0:3], off offset:256
	s_waitcnt lgkmcnt(0)
	v_pk_add_f32 v[6:7], v[32:33], v[8:9] op_sel_hi:[1,0] neg_lo:[0,1] neg_hi:[0,1]
	v_add_u32_e32 v0, s54, v214
	v_ashrrev_i32_e32 v1, 31, v0
	v_lshlrev_b64 v[0:1], 10, v[0:1]
	v_lshl_add_u64 v[12:13], v[0:1], 0, v[186:187]
	v_pk_add_f32 v[0:1], v[38:39], v[8:9] op_sel_hi:[1,0] neg_lo:[0,1] neg_hi:[0,1]
	v_pk_add_f32 v[2:3], v[36:37], v[8:9] op_sel_hi:[1,0] neg_lo:[0,1] neg_hi:[0,1]
	v_pk_mul_f32 v[4:5], v[8:9], v[2:3] op_sel:[1,0]
	v_pk_mul_f32 v[0:1], v[8:9], v[0:1] op_sel:[1,0]
	v_pk_mul_f32 v[10:11], v[8:9], v[6:7] op_sel:[1,0]
	v_pk_fma_f32 v[2:3], v[154:155], v[0:1], v[158:159]
	v_pk_fma_f32 v[0:1], v[152:153], v[4:5], v[156:157]
	v_pk_add_f32 v[4:5], v[34:35], v[8:9] op_sel_hi:[1,0] neg_lo:[0,1] neg_hi:[0,1]
	v_pk_mul_f32 v[4:5], v[8:9], v[4:5] op_sel:[1,0]
	s_and_b64 vcc, exec, s[12:13]
	v_pk_fma_f32 v[6:7], v[146:147], v[4:5], v[150:151]
	v_pk_fma_f32 v[4:5], v[144:145], v[10:11], v[148:149]
	v_lshl_add_u64 v[10:11], v[12:13], 2, s[28:29]
	s_cbranch_vccnz .LBB0_736
	global_store_dwordx4 v[10:11], v[0:3], off
	global_store_dwordx4 v[10:11], v[4:7], off offset:16

.LBB0_738:
	v_mov_b64_e32 v[8:9], v[174:175]
	v_cvt_pk_bf16_f32 v0, v0, v1
	v_cvt_pk_bf16_f32 v1, v2, v3
	v_cvt_pk_bf16_f32 v2, v4, v5
	v_cvt_pk_bf16_f32 v3, v6, v7
	global_store_dwordx4 v[12:13], v[0:3], off offset:256
	s_waitcnt lgkmcnt(0)
	v_pk_add_f32 v[6:7], v[88:89], v[8:9] op_sel_hi:[1,0] neg_lo:[0,1] neg_hi:[0,1]
	v_add_u32_e32 v0, s54, v216
	v_ashrrev_i32_e32 v1, 31, v0
	v_lshlrev_b64 v[0:1], 10, v[0:1]
	v_lshl_add_u64 v[12:13], v[0:1], 0, v[186:187]
	v_pk_add_f32 v[0:1], v[94:95], v[8:9] op_sel_hi:[1,0] neg_lo:[0,1] neg_hi:[0,1]
	v_pk_add_f32 v[2:3], v[92:93], v[8:9] op_sel_hi:[1,0] neg_lo:[0,1] neg_hi:[0,1]
	v_pk_mul_f32 v[4:5], v[8:9], v[2:3] op_sel:[1,0]
	v_pk_mul_f32 v[0:1], v[8:9], v[0:1] op_sel:[1,0]
	v_pk_mul_f32 v[10:11], v[8:9], v[6:7] op_sel:[1,0]
	v_pk_fma_f32 v[2:3], v[154:155], v[0:1], v[158:159]
	v_pk_fma_f32 v[0:1], v[152:153], v[4:5], v[156:157]
	v_pk_add_f32 v[4:5], v[90:91], v[8:9] op_sel_hi:[1,0] neg_lo:[0,1] neg_hi:[0,1]
	v_pk_mul_f32 v[4:5], v[8:9], v[4:5] op_sel:[1,0]
	s_and_b64 vcc, exec, s[12:13]
	v_pk_fma_f32 v[6:7], v[146:147], v[4:5], v[150:151]
	v_pk_fma_f32 v[4:5], v[144:145], v[10:11], v[148:149]
	v_lshl_add_u64 v[10:11], v[12:13], 2, s[28:29]
	s_cbranch_vccnz .LBB0_740
	global_store_dwordx4 v[10:11], v[0:3], off
	global_store_dwordx4 v[10:11], v[4:7], off offset:16

.LBB0_742:
	v_mov_b64_e32 v[8:9], v[224:225]
	v_cvt_pk_bf16_f32 v0, v0, v1
	v_cvt_pk_bf16_f32 v1, v2, v3
	v_cvt_pk_bf16_f32 v2, v4, v5
	v_cvt_pk_bf16_f32 v3, v6, v7
	global_store_dwordx4 v[12:13], v[0:3], off offset:256
	s_waitcnt lgkmcnt(0)
	v_pk_add_f32 v[6:7], v[64:65], v[8:9] op_sel_hi:[1,0] neg_lo:[0,1] neg_hi:[0,1]
	v_add_u32_e32 v0, s54, v218
	v_ashrrev_i32_e32 v1, 31, v0
	v_lshlrev_b64 v[0:1], 10, v[0:1]
	v_lshl_add_u64 v[12:13], v[0:1], 0, v[186:187]
	v_pk_add_f32 v[0:1], v[78:79], v[8:9] op_sel_hi:[1,0] neg_lo:[0,1] neg_hi:[0,1]
	v_pk_add_f32 v[2:3], v[76:77], v[8:9] op_sel_hi:[1,0] neg_lo:[0,1] neg_hi:[0,1]
	v_pk_mul_f32 v[4:5], v[8:9], v[2:3] op_sel:[1,0]
	v_pk_mul_f32 v[0:1], v[8:9], v[0:1] op_sel:[1,0]
	v_pk_mul_f32 v[10:11], v[8:9], v[6:7] op_sel:[1,0]
	v_pk_fma_f32 v[2:3], v[154:155], v[0:1], v[158:159]
	v_pk_fma_f32 v[0:1], v[152:153], v[4:5], v[156:157]
	v_pk_add_f32 v[4:5], v[66:67], v[8:9] op_sel_hi:[1,0] neg_lo:[0,1] neg_hi:[0,1]
	v_pk_mul_f32 v[4:5], v[8:9], v[4:5] op_sel:[1,0]
	s_and_b64 vcc, exec, s[12:13]
	v_pk_fma_f32 v[6:7], v[146:147], v[4:5], v[150:151]
	v_pk_fma_f32 v[4:5], v[144:145], v[10:11], v[148:149]
	v_lshl_add_u64 v[10:11], v[12:13], 2, s[28:29]
	s_cbranch_vccnz .LBB0_744
	global_store_dwordx4 v[10:11], v[0:3], off
	global_store_dwordx4 v[10:11], v[4:7], off offset:16

.LBB0_746:
	v_mov_b64_e32 v[8:9], v[226:227]
	v_cvt_pk_bf16_f32 v0, v0, v1
	v_cvt_pk_bf16_f32 v1, v2, v3
	v_cvt_pk_bf16_f32 v2, v4, v5
	v_cvt_pk_bf16_f32 v3, v6, v7
	global_store_dwordx4 v[12:13], v[0:3], off offset:256
	s_waitcnt lgkmcnt(0)
	v_pk_add_f32 v[6:7], v[112:113], v[8:9] op_sel_hi:[1,0] neg_lo:[0,1] neg_hi:[0,1]
	v_add_u32_e32 v0, s54, v220
	v_ashrrev_i32_e32 v1, 31, v0
	v_lshlrev_b64 v[0:1], 10, v[0:1]
	v_lshl_add_u64 v[12:13], v[0:1], 0, v[186:187]
	v_pk_add_f32 v[0:1], v[122:123], v[8:9] op_sel_hi:[1,0] neg_lo:[0,1] neg_hi:[0,1]
	v_pk_add_f32 v[2:3], v[120:121], v[8:9] op_sel_hi:[1,0] neg_lo:[0,1] neg_hi:[0,1]
	v_pk_mul_f32 v[4:5], v[8:9], v[2:3] op_sel:[1,0]
	v_pk_mul_f32 v[0:1], v[8:9], v[0:1] op_sel:[1,0]
	v_pk_mul_f32 v[10:11], v[8:9], v[6:7] op_sel:[1,0]
	v_pk_fma_f32 v[2:3], v[154:155], v[0:1], v[158:159]
	v_pk_fma_f32 v[0:1], v[152:153], v[4:5], v[156:157]
	v_pk_add_f32 v[4:5], v[114:115], v[8:9] op_sel_hi:[1,0] neg_lo:[0,1] neg_hi:[0,1]
	v_pk_mul_f32 v[4:5], v[8:9], v[4:5] op_sel:[1,0]
	s_and_b64 vcc, exec, s[12:13]
	v_pk_fma_f32 v[6:7], v[146:147], v[4:5], v[150:151]
	v_pk_fma_f32 v[4:5], v[144:145], v[10:11], v[148:149]
	v_lshl_add_u64 v[10:11], v[12:13], 2, s[28:29]
	s_cbranch_vccnz .LBB0_748
	global_store_dwordx4 v[10:11], v[0:3], off
	global_store_dwordx4 v[10:11], v[4:7], off offset:16

.LBB0_750:
	v_mov_b64_e32 v[8:9], v[238:239]
	v_cvt_pk_bf16_f32 v0, v0, v1
	v_cvt_pk_bf16_f32 v1, v2, v3
	v_cvt_pk_bf16_f32 v2, v4, v5
	v_cvt_pk_bf16_f32 v3, v6, v7
	global_store_dwordx4 v[12:13], v[0:3], off offset:256
	s_waitcnt lgkmcnt(0)
	v_pk_add_f32 v[6:7], v[108:109], v[8:9] op_sel_hi:[1,0] neg_lo:[0,1] neg_hi:[0,1]
	v_add_u32_e32 v0, s54, v222
	v_ashrrev_i32_e32 v1, 31, v0
	v_lshlrev_b64 v[0:1], 10, v[0:1]
	v_lshl_add_u64 v[12:13], v[0:1], 0, v[186:187]
	v_pk_add_f32 v[0:1], v[118:119], v[8:9] op_sel_hi:[1,0] neg_lo:[0,1] neg_hi:[0,1]
	v_pk_add_f32 v[2:3], v[116:117], v[8:9] op_sel_hi:[1,0] neg_lo:[0,1] neg_hi:[0,1]
	v_pk_mul_f32 v[4:5], v[8:9], v[2:3] op_sel:[1,0]
	v_pk_mul_f32 v[0:1], v[8:9], v[0:1] op_sel:[1,0]
	v_pk_mul_f32 v[10:11], v[8:9], v[6:7] op_sel:[1,0]
	v_pk_fma_f32 v[2:3], v[154:155], v[0:1], v[158:159]
	v_pk_fma_f32 v[0:1], v[152:153], v[4:5], v[156:157]
	v_pk_add_f32 v[4:5], v[110:111], v[8:9] op_sel_hi:[1,0] neg_lo:[0,1] neg_hi:[0,1]
	v_pk_mul_f32 v[4:5], v[8:9], v[4:5] op_sel:[1,0]
	s_and_b64 vcc, exec, s[12:13]
	v_pk_fma_f32 v[6:7], v[146:147], v[4:5], v[150:151]
	v_pk_fma_f32 v[4:5], v[144:145], v[10:11], v[148:149]
	v_lshl_add_u64 v[10:11], v[12:13], 2, s[28:29]
	s_cbranch_vccnz .LBB0_752
	global_store_dwordx4 v[10:11], v[0:3], off
	global_store_dwordx4 v[10:11], v[4:7], off offset:16
